# one static s_setprio 1 for waves 4-7 for the whole mixer phase (reset to 0 at its end)
# speedup vs baseline: 1.0084x; 1.0026x over previous
; #define LAS __attribute__((address_space(3)))
; __device__ __forceinline__ int opaque_tid(int wv) { int t = wv * 64 + (int)__builtin_amdgcn_mbcnt_hi(~0u, __builtin_amdgcn_mbcnt_lo(~0u, 0u)); asm volatile("" : "+v"(t)); return t; }
; __device__ __forceinline__ void mixer_phase(int wv, const Args& A, LAS unsigned char* lds) {
;     LAS int* itemw = (LAS int*)(lds + LDS_BYTES - 64);
;     unsigned* ctr = (unsigned*)(A.ws + WS_CTL);
;     constexpr int N_GP = 32, N_DP = 2048, N_DS = 32, N_GS = 128, NIT = N_GP + N_DP + N_DS + N_GS;
;     for (;;) {
;         __syncthreads();
;         if (opaque_tid(wv) == 0) *itemw = (int)atomicAdd(ctr, 1u);
;         __syncthreads();
;         int it = *itemw;
.LBB0_849:
	v_writelane_b32 v236, s86, 11
	s_or_b64 exec, exec, s[6:7]
	s_load_dwordx2 s[0:1], s[84:85], 0x28
	s_load_dwordx2 s[4:5], s[84:85], 0x48
	s_load_dwordx4 s[48:51], s[84:85], 0xd8
	s_waitcnt lgkmcnt(0)
	v_add_u32_e32 v0, 64, v178
	v_cmp_lt_i32_e32 vcc, v171, v0
	s_movk_i32 s96, 0x100
	v_writelane_b32 v236, s4, 12
	s_add_u32 s3, s48, 0x15020000
	v_cndmask_b32_e32 v1, v176, v171, vcc
	v_writelane_b32 v236, s5, 13
	v_writelane_b32 v236, s3, 14
	s_addc_u32 s3, s49, 0
	v_writelane_b32 v236, s3, 15
	v_writelane_b32 v236, s0, 16
	s_cmp_lg_u64 s[0:1], 0
	v_cmp_lt_i32_e32 vcc, v172, v0
	v_writelane_b32 v236, s1, 17
	s_cselect_b64 s[0:1], -1, 0
	s_add_u32 s3, s50, 0x324c1000
	v_writelane_b32 v236, s3, 18
	s_addc_u32 s3, s51, 0
	v_writelane_b32 v236, s3, 19
	s_add_u32 s3, s50, 0x34541000
	v_writelane_b32 v236, s3, 20
	s_addc_u32 s3, s51, 0
	s_add_u32 s76, s50, 0x365c1000
	s_addc_u32 s77, s51, 0
	v_writelane_b32 v236, s3, 21
	s_add_u32 s3, s50, 0x38641000
	v_writelane_b32 v236, s3, 22
	s_addc_u32 s3, s51, 0
	s_add_u32 s4, s50, 0x2a2c1000
	v_writelane_b32 v236, s3, 23
	s_addc_u32 s5, s51, 0
	v_writelane_b32 v236, s4, 24
	v_lshlrev_b32_e32 v171, 2, v1
	v_cndmask_b32_e32 v1, v176, v172, vcc
	v_writelane_b32 v236, s5, 25
	s_add_u32 s4, s50, 0x12d01000
	s_addc_u32 s5, s51, 0
	s_add_u32 s82, s50, 0x2081000
	v_writelane_b32 v236, s4, 26
	s_addc_u32 s83, s51, 0
	s_add_u32 s3, s50, 0x3d54d000
	v_writelane_b32 v236, s5, 27
	v_writelane_b32 v236, s3, 28
	s_addc_u32 s3, s51, 0
	s_add_u32 s84, s50, 0x2491000
	s_addc_u32 s85, s51, 0
	v_writelane_b32 v236, s3, 29
	s_add_u32 s3, s50, 0x3ea51000
	v_writelane_b32 v236, s3, 30
	s_addc_u32 s3, s51, 0
	s_add_u32 s86, s50, 0x2cb1000
	s_addc_u32 s87, s51, 0
	v_writelane_b32 v236, s3, 31
	s_add_u32 s3, s50, 0x3ec51000
	v_writelane_b32 v236, s3, 32
	s_addc_u32 s3, s51, 0
	v_cmp_lt_i32_e32 vcc, v173, v0
	v_writelane_b32 v236, s3, 33
	s_add_u32 s3, s48, 0x14c00000
	v_lshlrev_b32_e32 v172, 2, v1
	v_cndmask_b32_e32 v1, v176, v173, vcc
	v_cmp_lt_i32_e32 vcc, v174, v0
	v_writelane_b32 v236, s3, 34
	s_addc_u32 s3, s49, 0
	v_lshlrev_b32_e32 v173, 2, v1
	v_cndmask_b32_e32 v1, v176, v174, vcc
	v_cmp_lt_i32_e32 vcc, v175, v0
	v_writelane_b32 v236, s3, 35
	v_lshlrev_b32_e32 v174, 2, v1
	v_cndmask_b32_e32 v1, v176, v175, vcc
	v_cmp_lt_i32_e32 vcc, v177, v0
	v_writelane_b32 v236, s0, 36
	s_add_i32 s79, 0, 0x25fc0
	v_cndmask_b32_e32 v0, v176, v177, vcc
	v_writelane_b32 v236, s1, 37
	v_cndmask_b32_e64 v150, 0, 1, s[0:1]
	s_add_i32 s0, 0, 0x13000
	v_lshlrev_b32_e32 v175, 2, v1
	v_lshlrev_b32_e32 v176, 2, v0
	s_mov_b32 s49, 0
	v_mov_b32_e32 v1, 0
	v_mov_b32_e32 v151, 0xff800000
	s_movk_i32 s68, 0x400
	s_movk_i32 s71, 0x4c0
	s_movk_i32 s75, 0x2c0
	v_writelane_b32 v236, s0, 38
	v_mov_b32_e32 v152, 0x4c0
	s_movk_i32 s33, 0x5a
	s_mov_b32 s3, 0x3d800000
	s_mov_b32 s53, 0xff800000
	v_mov_b32_e32 v153, s79
	v_mov_b32_e32 v154, 0x3c845000
	v_mov_b32_e32 v155, 0x3c741000
	v_bfrev_b32_e32 v156, 1
	v_mov_b32_e32 v157, 0x2e00
	s_barrier
	v_writelane_b32 v236, s79, 39
	v_cmp_eq_u32_e32 vcc, 0, v170
	s_and_saveexec_b64 s[6:7], vcc
	v_mov_b32_e32 v237, 1
	s_nop 0
	global_atomic_add v237, v1, v237, s[50:51] sc0
	s_mov_b64 exec, s[6:7]
	v_readfirstlane_b32 s6, v170
	s_lshr_b32 s6, s6, 6
	s_cmp_ge_u32 s6, 4
	s_cbranch_scc0 .Lprio_done
	s_setprio 1
.Lprio_done:
	s_branch .LBB0_853
; #define LAS __attribute__((address_space(3)))
; __device__ __forceinline__ void gla_chain(int wv, const Args& A, LAS unsigned char* lds, int cidx0, int nsteps, int h, int sl, const float* S0, float* Sout) {
;     ...
;         for (int vbl = 0; vbl < 4; ++vbl) { h16x4 s4;
; #pragma unroll
;             for (int r = 0; r < 4; ++r) s4[r] = (h16)(Sacc[vbl][r] * scal[w * 16 + fq * 4 + r]);
;             *(LAS u32x2*)(STs + w136 + (vbl * 16 * 136 + w * 16) * 2) = __builtin_bit_cast(u32x2, s4); }
; #pragma unroll
;         for (int tt = 0; tt < 2; ++tt) { const int t = 2 * w + tt, ib = t >> 2, jb = t & 3; f32x4 a = {0.f, 0.f, 0.f, 0.f};
;             if (jb <= ib) {
; #pragma unroll
;                 for (int ks = 0; ks < 4; ++ks) { const h16x8 kf = *(const LAS h16x8*)(KTs + f136 + (jb * 16 * 136 + ks * 32) * 2), qf = *(const LAS h16x8*)(QTs + f136 + (ib * 16 * 136 + ks * 32) * 2);
;                     a = __builtin_amdgcn_mfma_f32_16x16x32_f16(kf, qf, a, 0, 0, 0); }
; #pragma unroll
;                 for (int r = 0; r < 4; ++r) if (jb * 16 + fq * 4 + r > ib * 16 + fr) a[r] = 0.f;
;             }
;             h16x4 a4; a4[0] = (h16)a[0]; a4[1] = (h16)a[1]; a4[2] = (h16)a[2]; a4[3] = (h16)a[3];
;             *(LAS u32x2*)(As + w72 + (ib * 16 * 72 + jb * 16) * 2) = __builtin_bit_cast(u32x2, a4); }
;         __syncthreads();
;         { const int ib = w >> 1;
; #pragma unroll
;             for (int j = 0; j < 2; ++j) { const int vbl = (w & 1) * 2 + j; f32x4 o = {0.f, 0.f, 0.f, 0.f};
; #pragma unroll
;                 for (int ks = 0; ks < 4; ++ks) { const h16x8 sf = *(const LAS h16x8*)(STs + f136 + (vbl * 16 * 136 + ks * 32) * 2), qf = *(const LAS h16x8*)(QTs + f136 + (ib * 16 * 136 + ks * 32) * 2);
;                     o = __builtin_amdgcn_mfma_f32_16x16x32_f16(sf, qf, o, 0, 0, 0); }
; #pragma unroll
;                 for (int ks = 0; ks < 2; ++ks) { const h16x8 af = *(const LAS h16x8*)(As + f72 + (ib * 16 * 72 + ks * 32) * 2);
;                     o = __builtin_amdgcn_mfma_f32_16x16x32_f16(voc[j][ks], af, o, 0, 0, 0); }
;                 h16x4 o4; o4[0] = (h16)o[0]; o4[1] = (h16)o[1]; o4[2] = (h16)o[2]; o4[3] = (h16)o[3];
;                 *(u32x2*)((char*)(ws + WS_MIX) + ((tok0 + ib * 16) * DM + 1024 + h * 256 + sl * 64 + vbl * 16) * 2 + g_go) = __builtin_bit_cast(u32x2, o4); } }
; #pragma unroll
;         for (int vbl = 0; vbl < 4; ++vbl) {
; #pragma unroll
.LBB0_850:
	s_lshl_b32 s0, s0, 2
	v_cvt_pk_f16_f32 v69, v71, v72
	v_cvt_pk_f16_f32 v68, v68, v70
	s_lshl_b64 s[6:7], s[34:35], 11
	s_or_b32 s0, s0, s1
	ds_write_b64 v169, v[68:69]
	s_waitcnt lgkmcnt(0)
	s_barrier
	ds_read_b128 v[68:71], v0
	s_or_b32 s8, s30, 0xff
	s_or_b64 s[6:7], s[6:7], s[28:29]
	s_ashr_i32 s1, s0, 31
	s_ashr_i32 s9, s8, 31
	s_or_b64 s[10:11], s[6:7], s[48:49]
	s_lshl_b64 s[0:1], s[0:1], 17
	v_readlane_b32 s6, v236, 34
	s_add_u32 s7, s6, s0
	v_readlane_b32 s0, v236, 35
	s_addc_u32 s12, s0, s1
	s_lshl_b32 s6, s58, 12
	s_lshl_b64 s[0:1], s[8:9], 17
	s_add_u32 s10, s10, s0
	ds_read_b128 v[72:75], v67 offset:54272
	ds_read_b128 v[76:79], v0 offset:64
	s_addc_u32 s9, s11, s1
	s_add_i32 s0, s59, 0
	v_add_u32_e32 v80, s0, v160
	v_add_u32_e32 v108, 0x15c00, v80
	ds_read_b128 v[80:83], v108 offset:64
	ds_read_b128 v[84:87], v66 offset:512
	s_waitcnt lgkmcnt(3)
	v_mfma_f32_16x16x32_f16 v[68:71], v[68:71], v[72:75], 0
	ds_read_b128 v[88:91], v0 offset:128
	ds_read_b128 v[92:95], v67 offset:54336
	ds_read_b128 v[96:99], v67 offset:54400
	s_or_b32 s8, s10, s5
	s_lshl_b64 s[0:1], s[8:9], 1
	s_waitcnt lgkmcnt(1)
	v_mfma_f32_16x16x32_f16 v[68:71], v[76:79], v[92:95], v[68:71]
	ds_read_b128 v[76:79], v0 offset:192
	v_pk_mul_f32 v[4:5], v[4:5], v[86:87]
	v_pk_mul_f32 v[2:3], v[2:3], v[84:85]
	s_waitcnt lgkmcnt(1)
	v_mfma_f32_16x16x32_f16 v[68:71], v[88:91], v[96:99], v[68:71]
	ds_read_b128 v[88:91], v67 offset:54464
	ds_read_b128 v[100:103], v0 offset:4352
	v_pk_mul_f32 v[12:13], v[12:13], v[86:87]
	v_pk_mul_f32 v[10:11], v[10:11], v[84:85]
	s_waitcnt lgkmcnt(1)
	v_mfma_f32_16x16x32_f16 v[66:69], v[76:79], v[88:91], v[68:71]
	ds_read_b128 v[76:79], v161
	ds_read_b128 v[104:107], v0 offset:4544
	s_bitset1_b32 s0, 11
	s_or_b32 s8, s10, s4
	s_waitcnt vmcnt(5) lgkmcnt(1)
	v_mfma_f32_16x16x32_f16 v[62:65], v[62:65], v[76:79], v[66:69]
	s_nop 2
	ds_read_b128 v[66:69], v161 offset:64
	ds_read_b128 v[108:111], v108
	v_pk_mul_f32 v[8:9], v[8:9], v[86:87]
	v_pk_mul_f32 v[6:7], v[6:7], v[84:85]
	s_waitcnt vmcnt(4) lgkmcnt(1)
	v_mfma_f32_16x16x32_f16 v[58:61], v[58:61], v[66:69], v[62:65]
	v_mul_f32_e64 v16, v16, v86
	v_mul_f32_e64 v17, v17, v87
	v_pk_mul_f32 v[14:15], v[14:15], v[84:85]
	ds_read_b128 v[62:65], v0 offset:4416
	v_mfma_f32_16x16x32_f16 v[70:73], v[100:103], v[72:75], 0
	ds_read_b128 v[100:103], v0 offset:4480
	v_lshlrev_b32_e32 v0, 2, v159
	v_lshl_or_b32 v0, v158, 12, v0
	s_waitcnt lgkmcnt(1)
	v_mfma_f32_16x16x32_f16 v[62:65], v[62:65], v[92:95], v[70:73]
	s_waitcnt lgkmcnt(0)
	v_mfma_f32_16x16x32_f16 v[62:65], v[100:103], v[96:99], v[62:65]
	v_mfma_f32_16x16x32_f16 v[62:65], v[104:107], v[88:91], v[62:65]
	s_waitcnt vmcnt(3)
	v_mfma_f32_16x16x32_f16 v[50:53], v[50:53], v[76:79], v[62:65]
	v_mfma_f32_16x16x32_f16 v[2:5], v[108:111], v[46:49], v[2:5]
	v_cvt_pk_f16_f32 v47, v60, v61
	v_cvt_pk_f16_f32 v46, v58, v59
	v_mfma_f32_16x16x32_f16 v[10:13], v[108:111], v[38:41], v[10:13]
	v_lshl_add_u64 v[38:39], v[138:139], 0, s[0:1]
	s_lshl_b64 s[0:1], s[8:9], 1
	s_bitset1_b32 s0, 11
	v_mfma_f32_16x16x32_f16 v[6:9], v[108:111], v[22:25], v[6:9]
	v_lshl_add_u64 v[22:23], v[138:139], 0, s[0:1]
	s_lshl_b32 s0, s28, 2
	s_add_u32 s0, s7, s0
	s_waitcnt vmcnt(2)
	v_mfma_f32_16x16x32_f16 v[50:53], v[54:57], v[66:69], v[50:53]
	s_addc_u32 s1, s12, 0
	s_ashr_i32 s7, s6, 31
	global_store_dwordx2 v[38:39], v[46:47], off
	v_mfma_f32_16x16x32_f16 v[2:5], v[80:83], v[42:45], v[2:5]
	v_mfma_f32_16x16x32_f16 v[14:17], v[108:111], v[30:33], v[14:17]
	s_nop 2
	v_cvt_pk_f16_f32 v31, v52, v53
	v_cvt_pk_f16_f32 v30, v50, v51
	global_store_dwordx2 v[22:23], v[30:31], off
	v_mfma_f32_16x16x32_f16 v[6:9], v[80:83], v[18:21], v[6:9]
	v_lshl_add_u64 v[18:19], s[0:1], 0, v[0:1]
	v_lshl_add_u64 v[18:19], s[6:7], 2, v[18:19]
	v_mfma_f32_16x16x32_f16 v[10:13], v[80:83], v[34:37], v[10:13]
	v_mfma_f32_16x16x32_f16 v[14:17], v[80:83], v[26:29], v[14:17]
	global_store_dword v[18:19], v2, off
	global_store_dword v[18:19], v3, off offset:1024
	global_store_dword v[18:19], v4, off offset:2048
	global_store_dword v[18:19], v5, off offset:3072
	s_nop 2
	global_store_dword v[18:19], v10, off offset:64
	global_store_dword v[18:19], v11, off offset:1088
	global_store_dword v[18:19], v12, off offset:2112
	global_store_dword v[18:19], v13, off offset:3136
	global_store_dword v[18:19], v14, off offset:128
	global_store_dword v[18:19], v15, off offset:1152
	global_store_dword v[18:19], v16, off offset:2176
	global_store_dword v[18:19], v17, off offset:3200
	global_store_dword v[18:19], v6, off offset:192
	global_store_dword v[18:19], v7, off offset:1216
	global_store_dword v[18:19], v8, off offset:2240
	global_store_dword v[18:19], v9, off offset:3264
	s_barrier

; __device__ __forceinline__ unsigned xb_add(unsigned* p, unsigned v) { return __hip_atomic_fetch_add(p, v, __ATOMIC_RELAXED, __HIP_MEMORY_SCOPE_AGENT); }
; __device__ __forceinline__ void xcd_barrier(const XcdBarrier& b) {
;     asm volatile("s_waitcnt vmcnt(0)" ::: "memory");
;     __syncthreads();
;     if (threadIdx.x == 0) {
;         unsigned* bar = b.bar;
;         __builtin_amdgcn_s_waitcnt(0);
;         unsigned nloc = b.st[0], nx = b.st[1];
;         if (nloc == 0u) { xcd_barrier_complete(bar, b.x, nloc, nx); b.st[0] = nloc; b.st[1] = nx; }
;         const unsigned old = xb_add(&bar[XB_XSUB(b.x)], 1u);
.LBB0_2068:
	s_setprio 0
	s_waitcnt vmcnt(0)
	v_readlane_b32 s86, v236, 0
	v_readlane_b32 s87, v236, 1
	s_barrier
	s_and_saveexec_b64 s[6:7], s[86:87]
	v_readlane_b32 s82, v236, 8
	v_readlane_b32 s83, v236, 9
	v_readlane_b32 s81, v236, 10
	v_readlane_b32 s84, v236, 11
	s_cbranch_execz .LBB0_2120
	s_add_i32 s0, 0, 0x25fe0
	v_mov_b32_e32 v0, s0
	s_waitcnt vmcnt(0) expcnt(0) lgkmcnt(0)
	ds_read_b32 v2, v0
	s_add_i32 s0, 0, 0x25fe4
	v_mov_b32_e32 v0, s0
	ds_read_b32 v0, v0
	s_waitcnt lgkmcnt(1)
	v_cmp_ne_u32_e32 vcc, 0, v2
	s_cbranch_vccnz .LBB0_2084
	s_add_u32 s8, s44, 0x3ea4d200
	s_addc_u32 s9, s45, 0
	s_add_u32 s10, s44, 0x3ea4d400
	s_addc_u32 s11, s45, 0
	s_add_u32 s12, s44, 0x3ea4d500
	s_addc_u32 s13, s45, 0
	s_add_u32 s14, s44, 0x3ea4d600
	s_addc_u32 s15, s45, 0
	s_add_u32 s16, s44, 0x3ea4d700
	s_addc_u32 s17, s45, 0
	s_add_u32 s18, s44, 0x3ea4d800
	s_addc_u32 s19, s45, 0
	s_add_u32 s20, s44, 0x3ea4d900
	s_addc_u32 s21, s45, 0
	s_add_u32 s22, s44, 0x3ea4da00
	s_addc_u32 s23, s45, 0
	s_add_u32 s24, s44, 0x3ea4db00
	s_addc_u32 s25, s45, 0
	s_add_u32 s26, s44, 0x3ea4dc00
	s_addc_u32 s27, s45, 0
	s_add_u32 s28, s44, 0x3ea4dd00
	s_addc_u32 s29, s45, 0
	s_add_u32 s30, s44, 0x3ea4de00
	s_addc_u32 s31, s45, 0
	s_add_u32 s34, s44, 0x3ea4df00
	s_addc_u32 s35, s45, 0
	s_add_u32 s36, s44, 0x3ea4e000
	s_addc_u32 s37, s45, 0
	s_add_u32 s38, s44, 0x3ea4e100
	s_addc_u32 s39, s45, 0
	s_add_u32 s40, s44, 0x3ea4e200
	s_addc_u32 s41, s45, 0
	s_mul_i32 s0, s47, s84
	s_add_u32 s42, s44, 0x3ea4e300
	s_mul_i32 s0, s0, s46
	s_addc_u32 s43, s45, 0
	s_mov_b32 s1, 1
	v_mov_b32_e32 v16, 0
	s_branch .LBB0_2072
